# attention unit prologue: bias-table loads overlap the K/V/Q tile loads (wait deferred)
# baseline (speedup 1.0000x reference)
; #define LAS __attribute__((address_space(3)))
; #define EXPALL(PF) do { _Pragma("unroll") for (int s_ = 0; s_ < 16 * NQT; ++s_) EXP1(s_); PACK16(PF, 0, 0); PACK16(PF, 0, 1); if (NQT > 1) { PACK16(PF, 1, 0); PACK16(PF, 1, 1); } } while (0)
; template <bool SAMPLE> __device__ __forceinline__ void attn_unit16(const Ctx& c, LAS unsigned char* lds, int b, int h, int qb, int wave_s) {
;     ...
;     if (SAMPLE) { load_kv(0, true); load_kv(0, false); store_k(0); store_v(0); load_kv(1, true); store_k(1); }
;     else { load_kv(0, true); const u32x4 k0a = kreg[0], k0b = kreg[1];
;       load_kv(0, false); load_kv(1, true);
;       LAS unsigned char* kb0 = lds + lrow * A_RSK + lck * 16; *(LAS u32x4*)kb0 = k0a; *(LAS u32x4*)(kb0 + 128) = k0b;
;       store_v(0); store_k(1); }
;     __syncthreads();
;     if (active) { QK16(0); MAX16(0); EXPALL(pfa); }
.LBB0_831:
	s_or_b64 exec, exec, s[2:3]
	v_cmp_lt_i32_e32 vcc, s67, v44
	s_lshl_b32 s2, s80, 2
	s_nop 0
	v_cndmask_b32_e64 v2, 0, 16, vcc
	v_add_u32_e32 v0, v0, v2
	v_lshl_or_b32 v0, v0, 3, s80
	v_lshl_add_u64 v[2:3], v[0:1], 2, s[48:49]
	v_mov_b32_e32 v0, s2
	global_load_dword v56, v[2:3], off
	s_nop 0
	global_load_dword v57, v0, s[48:49] offset:480
.LBB0_832:
	s_or_b64 exec, exec, s[0:1]
	s_lshr_b32 s56, s45, 2
	s_bfe_u32 s0, s51, 0x20007
	s_ashr_i32 s16, s44, 3
	s_xor_b32 s2, s56, 63
	s_xor_b32 s63, s0, 2
	s_lshl_b32 s0, s2, 7
	s_lshl_b32 s1, s63, 5
	s_ashr_i32 s17, s16, 31
	s_or_b32 s86, s1, s0
	s_lshl_b64 s[16:17], s[16:17], 13
	s_bfe_u32 s81, s51, 0x10006
	s_or_b32 s62, s16, s86
	s_lshl_b32 s3, s80, 8
	s_add_u32 s40, s92, s3
	s_addc_u32 s41, s93, 0
	s_lshl_b32 s3, s81, 7
	v_bfe_u32 v210, v44, 4, 2
	s_add_u32 s42, s40, s3
	v_ashrrev_i32_e32 v2, 3, v44
	s_addc_u32 s43, s41, 0
	v_lshlrev_b32_e32 v0, 4, v210
	v_ashrrev_i32_e32 v3, 31, v2
	v_lshl_add_u64 v[20:21], s[42:43], 0, v[0:1]
	v_mad_i64_i32 v[4:5], s[42:43], s44, v207, v[2:3]
	v_lshlrev_b64 v[4:5], 8, v[4:5]
	v_lshlrev_b32_e32 v10, 4, v44
	v_lshl_add_u64 v[6:7], s[4:5], 0, v[4:5]
	s_waitcnt vmcnt(2)
	v_and_b32_e32 v46, 0x70, v10
	v_mov_b32_e32 v47, v1
	v_lshl_add_u64 v[10:11], v[6:7], 0, v[46:47]
	v_and_b32_e32 v45, 15, v44
	global_load_dwordx4 v[36:39], v[10:11], off
	global_load_dwordx4 v[40:43], v[10:11], off offset:128
	v_lshl_add_u64 v[4:5], s[6:7], 0, v[4:5]
	v_add_co_u32_e32 v10, vcc, s69, v10
	v_or_b32_e32 v8, s62, v45
	v_mov_b32_e32 v9, s17
	v_lshl_add_u64 v[12:13], v[4:5], 0, v[46:47]
	v_addc_co_u32_e32 v11, vcc, 0, v11, vcc
	global_load_dwordx4 v[4:7], v[12:13], off
	s_nop 0
	global_load_dwordx4 v[12:15], v[12:13], off offset:128
	s_nop 0
	global_load_dwordx4 v[28:31], v[10:11], off
	global_load_dwordx4 v[32:35], v[10:11], off offset:128
	v_lshlrev_b64 v[22:23], 11, v[8:9]
	v_lshl_add_u64 v[16:17], v[20:21], 0, v[22:23]
	v_or_b32_e32 v22, 0x8000, v22
	v_lshl_add_u64 v[24:25], v[20:21], 0, v[22:23]
	global_load_dwordx4 v[8:11], v[16:17], off
	s_nop 0
	global_load_dwordx4 v[16:19], v[16:17], off offset:64
	s_nop 0
	global_load_dwordx4 v[20:23], v[24:25], off
	s_nop 0
	global_load_dwordx4 v[24:27], v[24:25], off offset:64
	v_mul_lo_u32 v47, v2, s70
	v_lshlrev_b32_e32 v48, 4, v2
	v_add_u32_e32 v47, 0, v47
	v_add_u32_e32 v211, v47, v46
	v_add_u32_e32 v47, v47, v48
	s_add_i32 s3, s3, 0
	v_add_u32_e32 v213, v47, v46
	v_cmp_gt_i32_e32 vcc, s66, v44
	s_and_saveexec_b64 s[100:101], vcc
	s_waitcnt vmcnt(10)
	v_sub_f32_e32 v57, v56, v57
	v_lshlrev_b32_e32 v58, 2, v44
	v_mul_f32_e32 v57, 0x3fb8aa3b, v57
	v_add_u32_e32 v58, 0x11800, v58
	ds_write_b32 v58, v57
	s_or_b64 exec, exec, s[100:101]
	s_waitcnt vmcnt(9)
	ds_write_b128 v211, v[36:39]
	s_waitcnt vmcnt(8)
	ds_write_b128 v211, v[40:43] offset:128
	s_waitcnt vmcnt(7)
	ds_write_b128 v213, v[4:7] offset:17408
	s_waitcnt vmcnt(6)
	ds_write_b128 v213, v[12:15] offset:17536
	s_waitcnt vmcnt(5)
	ds_write_b128 v211, v[28:31] offset:35840
	s_waitcnt vmcnt(4)
	ds_write_b128 v211, v[32:35] offset:35968
	v_mov_b32_e32 v36, s3
	v_mad_u32_u24 v36, v45, s70, v36
	v_add_u32_e32 v214, v36, v0
	s_waitcnt lgkmcnt(0)
	s_barrier
	ds_read_b128 v[36:39], v214
	ds_read_b128 v[40:43], v214 offset:64
	s_waitcnt vmcnt(3) lgkmcnt(1)
	v_mfma_f32_16x16x32_bf16 v[46:49], v[36:39], v[8:11], 0
	s_waitcnt vmcnt(1)
	v_mfma_f32_16x16x32_bf16 v[36:39], v[36:39], v[20:23], 0
	s_waitcnt lgkmcnt(0)
	v_mfma_f32_16x16x32_bf16 v[48:51], v[40:43], v[16:19], v[46:49]
	s_waitcnt vmcnt(0)
	v_mfma_f32_16x16x32_bf16 v[52:55], v[40:43], v[24:27], v[36:39]
	v_mov_b32_e32 v0, s71
	ds_read_b32 v0, v0
	v_mov_b32_e32 v46, 0xff800000
	s_waitcnt lgkmcnt(0)
	s_nop 1
	v_pk_add_f32 v[42:43], v[48:49], v[0:1] op_sel_hi:[1,0]
	v_pk_add_f32 v[40:41], v[50:51], v[0:1] op_sel_hi:[1,0]
	v_pk_add_f32 v[38:39], v[52:53], v[0:1] op_sel_hi:[1,0]
	v_pk_add_f32 v[36:37], v[54:55], v[0:1] op_sel_hi:[1,0]
	v_max3_f32 v0, v42, v43, v40
	v_max_f32_e32 v47, 0xff800000, v41
	v_max3_f32 v47, v0, v46, v47
	v_max3_f32 v0, v38, v39, v36
	v_max_f32_e32 v48, 0xff800000, v37
	v_max3_f32 v0, v0, v46, v48
	v_max_f32_e64 v48, |v47|, |v0|
	v_cmp_lt_f32_e32 vcc, s72, v48
	s_cbranch_vccz .LBB0_834
	s_mov_b32 s98, 1
	v_and_b32_e32 v48, 64, v212
	v_xor_b32_e32 v46, 16, v212
	v_add_u32_e32 v48, 64, v48
	v_cmp_lt_i32_e32 vcc, v46, v48
	v_xor_b32_e32 v49, 32, v212
	s_nop 0
	v_cndmask_b32_e32 v46, v212, v46, vcc
	v_lshlrev_b32_e32 v46, 2, v46
	ds_bpermute_b32 v50, v46, v47
	ds_bpermute_b32 v46, v46, v0
	v_cmp_lt_i32_e32 vcc, v49, v48
	v_max_f32_e32 v0, v0, v0
	v_max_f32_e32 v47, v47, v47
	v_cndmask_b32_e32 v48, v212, v49, vcc
	s_waitcnt lgkmcnt(0)
	v_max_f32_e32 v46, v46, v46
	v_lshlrev_b32_e32 v48, 2, v48
	v_max_f32_e32 v49, v50, v50
	v_max_f32_e32 v0, v0, v46
	v_max_f32_e32 v47, v47, v49
	ds_bpermute_b32 v46, v48, v0
	ds_bpermute_b32 v49, v48, v47
	s_waitcnt lgkmcnt(1)
	v_max_f32_e32 v46, v46, v46
	s_waitcnt lgkmcnt(0)
	v_max_f32_e32 v48, v49, v49
	v_max_f32_e32 v0, v0, v46
	v_max_f32_e32 v47, v47, v48
	v_cmp_gt_f32_e64 vcc, |v0|, s72
	s_nop 1
	v_cndmask_b32_e32 v197, 0, v0, vcc
	v_cmp_gt_f32_e64 vcc, |v47|, s72
	v_exp_f32_e64 v201, -v197
	v_sub_f32_e32 v0, 0xff800000, v197
	v_cndmask_b32_e32 v196, 0, v47, vcc
	v_exp_f32_e64 v200, -v196
	v_sub_f32_e32 v42, v42, v196
	v_sub_f32_e32 v43, v43, v196
	v_sub_f32_e32 v40, v40, v196
	v_sub_f32_e32 v41, v41, v196
	v_sub_f32_e32 v46, 0xff800000, v196
	v_sub_f32_e32 v38, v38, v197
	v_sub_f32_e32 v39, v39, v197
	v_sub_f32_e32 v36, v36, v197
	v_sub_f32_e32 v37, v37, v197
	v_mov_b32_e32 v47, v0
	v_mov_b32_e32 v48, v0
	v_mov_b32_e32 v49, v0
	s_branch .LBB0_835
